# RWKV scan: per-step 8-lane output reductions of 4 steps merged into one transposed reduce (cndmask + dpp + row_shr:4) and one exec-masked write pair per 4 steps
# speedup vs baseline: 1.0127x; 1.0063x over previous
; __device__ __forceinline__ void phase_rwkv(KP P, int l_, unsigned char* shm) {
;     ...
;                 f32x4 Aw0, Aw1, Akk0, Akk1, Ab0, Ab1, Ak0, Ak1, Ar0, Ar1; float Ava, Avb;
;                 f32x4 Bw0, Bw1, Bkk0, Bkk1, Bb0, Bb1, Bk0, Bk1, Br0, Br1; float Bva, Bvb;
;                 RW_LD(A, 0);
; #pragma unroll 2
;                 for (int tl = 0; tl < T; tl += 2) {
;                     RW_LD(B, tl + 1);
;                     RW_STEP(A, tl);
;                     RW_LD(A, tl + 2);
;                     RW_STEP(B, tl + 1);
;                 }
.LBB0_2515:
	s_and_b32 s1, s42, 1
	s_waitcnt vmcnt(26)
	v_cndmask_b32_e64 v0, 0, 1, s[78:79]
	s_mov_b32 s0, 0xa000
	s_mul_i32 s1, s1, 0xa000
	s_mul_i32 s43, s42, 0xab
	v_lshl_or_b32 v253, v0, 13, v173
	v_and_b32_e32 v187, 3, v228
	v_lshl_add_u32 v253, v187, 8, v253
	v_add_u32_e32 v253, 0x1e000, v253
	s_mov_b32 s98, 0xaaaaaaaa
	s_mov_b32 s99, 0xaaaaaaaa
	s_mov_b32 s100, 0xcccccccc
	s_mov_b32 s101, 0xcccccccc
	v_mul_lo_u32 v0, v0, s0
	s_bfe_u32 s43, s43, 0x70009
	s_waitcnt vmcnt(17)
	v_add_u32_e32 v14, s1, v156
	v_or_b32_e32 v235, v174, v0
	s_mul_i32 s43, s43, 3
	s_waitcnt vmcnt(12)
	ds_read_b128 v[10:13], v14
	ds_read_b128 v[0:3], v14 offset:16
	s_waitcnt vmcnt(0)
	ds_read_b128 v[38:41], v14 offset:8192
	ds_read_b128 v[34:37], v14 offset:8208
	ds_read_b128 v[26:29], v14 offset:16384
	ds_read_b128 v[6:9], v14 offset:16400
	ds_read_b128 v[30:33], v14 offset:24576
	ds_read_b128 v[22:25], v14 offset:24592
	s_sub_i32 s43, s42, s43
	s_and_b32 s43, s43, 0xff
	s_lshl_b32 s43, s43, 13
	s_add_i32 s43, s43, 0
	v_lshl_add_u32 v4, v123, 2, s43
	v_add_u32_e32 v4, 0x14000, v4
	s_mul_hi_u32 s0, s42, 0xaaaaaaab
	ds_read2_b32 v[106:107], v4 offset1:32
	ds_read_b128 v[18:21], v14 offset:32768
	ds_read_b128 v[14:17], v14 offset:32784
	s_lshr_b32 s0, s0, 1
	s_mulk_i32 s0, 0xa000
	s_add_i32 s43, s0, 0
	s_mov_b32 s52, -2
	v_mov_b32_e32 v252, v175
	s_waitcnt lgkmcnt(2)
	s_branch .LBB0_2517
.LBB0_2516:
	s_add_i32 s52, s52, 4
	v_add_u32_e32 v253, 0x400, v253
	v_add_u32_e32 v235, 0x400, v235
	s_cmp_gt_u32 s52, 29
	v_add_u32_e32 v252, 0x400, v252
	s_cbranch_scc1 .LBB0_2489
.LBB0_2517:
	v_pk_mul_f32 v[110:111], v[40:41], v[92:93]
	v_pk_mul_f32 v[40:41], v[40:41], v[100:101]
	v_pk_fma_f32 v[110:111], v[38:39], v[90:91], v[110:111]
	v_pk_fma_f32 v[38:39], v[38:39], v[98:99], v[40:41]
	v_pk_fma_f32 v[40:41], v[36:37], v[96:97], v[110:111]
	v_pk_fma_f32 v[36:37], v[36:37], v[104:105], v[38:39]
	v_pk_fma_f32 v[40:41], v[34:35], v[94:95], v[40:41]
	v_pk_fma_f32 v[34:35], v[34:35], v[102:103], v[36:37]
	v_add_f32_e32 v36, v40, v41
	v_add_f32_e32 v34, v34, v35
	ds_read_b128 v[62:65], v235
	v_add_f32_dpp v35, v36, v36 quad_perm:[1,0,3,2] row_mask:0xf bank_mask:0xf bound_ctrl:1
	v_add_f32_dpp v34, v34, v34 quad_perm:[1,0,3,2] row_mask:0xf bank_mask:0xf bound_ctrl:1
	ds_read_b128 v[50:53], v235 offset:16
	ds_read_b128 v[78:81], v235 offset:8192
	ds_read_b128 v[74:77], v235 offset:8208
	ds_read_b128 v[66:69], v235 offset:16384
	ds_read_b128 v[54:57], v235 offset:16400
	ds_read_b128 v[70:73], v235 offset:24576
	ds_read_b128 v[58:61], v235 offset:24592
	ds_read_b128 v[46:49], v235 offset:32768
	ds_read_b128 v[42:45], v235 offset:32784
	v_add_f32_dpp v35, v35, v35 quad_perm:[2,3,0,1] row_mask:0xf bank_mask:0xf bound_ctrl:1
	v_add_f32_dpp v36, v34, v34 quad_perm:[2,3,0,1] row_mask:0xf bank_mask:0xf bound_ctrl:1
	v_add_u32_e32 v186, s43, v252
	v_add_f32_dpp v34, v35, v35 row_half_mirror row_mask:0xf bank_mask:0xf bound_ctrl:1
	v_add_f32_dpp v36, v36, v36 row_half_mirror row_mask:0xf bank_mask:0xf bound_ctrl:1
	v_pk_mul_f32 v[38:39], v[26:27], v[34:35] op_sel_hi:[1,0] neg_lo:[0,1] neg_hi:[0,1]
	v_pk_mul_f32 v[26:27], v[26:27], v[36:37] op_sel_hi:[1,0] neg_lo:[0,1] neg_hi:[0,1]
	v_pk_fma_f32 v[38:39], v[10:11], v[90:91], v[38:39]
	v_pk_fma_f32 v[10:11], v[10:11], v[98:99], v[26:27]
	s_waitcnt lgkmcnt(13)
	v_pk_fma_f32 v[110:111], v[30:31], v[106:107], v[38:39] op_sel_hi:[1,0,1]
	v_pk_fma_f32 v[98:99], v[30:31], v[106:107], v[10:11] op_sel:[0,1,0]
	v_pk_mul_f32 v[10:11], v[28:29], v[34:35] op_sel_hi:[1,0] neg_lo:[0,1] neg_hi:[0,1]
	v_pk_mul_f32 v[170:171], v[28:29], v[36:37] op_sel_hi:[1,0] neg_lo:[0,1] neg_hi:[0,1]
	ds_read2_b32 v[108:109], v186 offset1:32
	v_pk_fma_f32 v[10:11], v[12:13], v[92:93], v[10:11]
	v_pk_fma_f32 v[170:171], v[12:13], v[100:101], v[170:171]
	v_pk_fma_f32 v[92:93], v[32:33], v[106:107], v[10:11] op_sel_hi:[1,0,1]
	v_pk_fma_f32 v[100:101], v[32:33], v[106:107], v[170:171] op_sel:[0,1,0]
	v_pk_mul_f32 v[10:11], v[6:7], v[34:35] op_sel_hi:[1,0] neg_lo:[0,1] neg_hi:[0,1]
	v_pk_mul_f32 v[6:7], v[6:7], v[36:37] op_sel_hi:[1,0] neg_lo:[0,1] neg_hi:[0,1]
	v_pk_fma_f32 v[10:11], v[0:1], v[94:95], v[10:11]
	v_pk_fma_f32 v[0:1], v[0:1], v[102:103], v[6:7]
	s_waitcnt lgkmcnt(13)
	v_pk_fma_f32 v[94:95], v[22:23], v[106:107], v[10:11] op_sel_hi:[1,0,1]
	v_pk_fma_f32 v[102:103], v[22:23], v[106:107], v[0:1] op_sel:[0,1,0]
	v_pk_mul_f32 v[0:1], v[8:9], v[34:35] op_sel_hi:[1,0] neg_lo:[0,1] neg_hi:[0,1]
	v_pk_mul_f32 v[170:171], v[8:9], v[36:37] op_sel_hi:[1,0] neg_lo:[0,1] neg_hi:[0,1]
	v_pk_fma_f32 v[0:1], v[2:3], v[96:97], v[0:1]
	v_pk_fma_f32 v[170:171], v[2:3], v[104:105], v[170:171]
	v_pk_fma_f32 v[96:97], v[24:25], v[106:107], v[0:1] op_sel_hi:[1,0,1]
	v_pk_fma_f32 v[104:105], v[24:25], v[106:107], v[170:171] op_sel:[0,1,0]
	s_waitcnt lgkmcnt(11)
	v_pk_mul_f32 v[2:3], v[20:21], v[100:101]
	v_pk_mul_f32 v[0:1], v[20:21], v[92:93]
	v_pk_fma_f32 v[2:3], v[18:19], v[98:99], v[2:3]
	v_pk_fma_f32 v[0:1], v[18:19], v[110:111], v[0:1]
	v_pk_fma_f32 v[8:9], v[16:17], v[104:105], v[2:3]
	v_pk_fma_f32 v[6:7], v[16:17], v[96:97], v[0:1]
	v_pk_fma_f32 v[8:9], v[14:15], v[102:103], v[8:9]
	v_pk_fma_f32 v[6:7], v[14:15], v[94:95], v[6:7]
	v_add_f32_e32 v158, v8, v9
	v_add_f32_e32 v157, v6, v7
	s_waitcnt lgkmcnt(6)
	v_pk_mul_f32 v[106:107], v[80:81], v[92:93]
	v_pk_mul_f32 v[80:81], v[80:81], v[100:101]
	v_pk_fma_f32 v[106:107], v[78:79], v[110:111], v[106:107]
	v_pk_fma_f32 v[78:79], v[78:79], v[98:99], v[80:81]
	s_waitcnt lgkmcnt(5)
	v_pk_fma_f32 v[80:81], v[76:77], v[96:97], v[106:107]
	v_pk_fma_f32 v[76:77], v[76:77], v[104:105], v[78:79]
	v_pk_fma_f32 v[80:81], v[74:75], v[94:95], v[80:81]
	v_pk_fma_f32 v[74:75], v[74:75], v[102:103], v[76:77]
	v_add_f32_e32 v4, v80, v81
	v_add_f32_e32 v74, v74, v75
	s_waitcnt lgkmcnt(0)
; __device__ __forceinline__ void phase_rwkv(KP P, int l_, unsigned char* shm) {
;     ...
;                 f32x4 Aw0, Aw1, Akk0, Akk1, Ab0, Ab1, Ak0, Ak1, Ar0, Ar1; float Ava, Avb;
;                 f32x4 Bw0, Bw1, Bkk0, Bkk1, Bb0, Bb1, Bk0, Bk1, Br0, Br1; float Bva, Bvb;
;                 RW_LD(A, 0);
; #pragma unroll 2
;                 for (int tl = 0; tl < T; tl += 2) {
;                     RW_LD(B, tl + 1);
;                     RW_STEP(A, tl);
;                     RW_LD(A, tl + 2);
;                     RW_STEP(B, tl + 1);
;                 }
	v_add_f32_dpp v4, v4, v4 quad_perm:[1,0,3,2] row_mask:0xf bank_mask:0xf bound_ctrl:1
	v_add_f32_dpp v74, v74, v74 quad_perm:[1,0,3,2] row_mask:0xf bank_mask:0xf bound_ctrl:1
	ds_read_b128 v[22:25], v235 offset:256
	ds_read_b128 v[10:13], v235 offset:272
	ds_read_b128 v[38:41], v235 offset:8448
	ds_read_b128 v[34:37], v235 offset:8464
	ds_read_b128 v[26:29], v235 offset:16640
	ds_read_b128 v[14:17], v235 offset:16656
	ds_read_b128 v[30:33], v235 offset:24832
	ds_read_b128 v[18:21], v235 offset:24848
	ds_read_b128 v[6:9], v235 offset:33024
	ds_read_b128 v[0:3], v235 offset:33040
	ds_read2_b32 v[90:91], v186 offset0:64 offset1:96
	v_add_f32_dpp v4, v4, v4 quad_perm:[2,3,0,1] row_mask:0xf bank_mask:0xf bound_ctrl:1
	v_add_f32_dpp v74, v74, v74 quad_perm:[2,3,0,1] row_mask:0xf bank_mask:0xf bound_ctrl:1
	s_nop 0
	v_add_f32_dpp v4, v4, v4 row_half_mirror row_mask:0xf bank_mask:0xf bound_ctrl:1
	v_add_f32_dpp v74, v74, v74 row_half_mirror row_mask:0xf bank_mask:0xf bound_ctrl:1
	v_pk_mul_f32 v[78:79], v[66:67], v[4:5] op_sel_hi:[1,0] neg_lo:[0,1] neg_hi:[0,1]
	v_pk_mul_f32 v[66:67], v[66:67], v[74:75] op_sel_hi:[1,0] neg_lo:[0,1] neg_hi:[0,1]
	v_pk_fma_f32 v[78:79], v[62:63], v[110:111], v[78:79]
	v_pk_fma_f32 v[62:63], v[62:63], v[98:99], v[66:67]
	v_pk_fma_f32 v[106:107], v[70:71], v[108:109], v[78:79] op_sel_hi:[1,0,1]
	v_pk_fma_f32 v[98:99], v[70:71], v[108:109], v[62:63] op_sel:[0,1,0]
	v_pk_mul_f32 v[62:63], v[68:69], v[4:5] op_sel_hi:[1,0] neg_lo:[0,1] neg_hi:[0,1]
	v_pk_mul_f32 v[170:171], v[68:69], v[74:75] op_sel_hi:[1,0] neg_lo:[0,1] neg_hi:[0,1]
	v_pk_fma_f32 v[62:63], v[64:65], v[92:93], v[62:63]
	v_pk_fma_f32 v[170:171], v[64:65], v[100:101], v[170:171]
	v_pk_fma_f32 v[110:111], v[72:73], v[108:109], v[62:63] op_sel_hi:[1,0,1]
	v_pk_fma_f32 v[112:113], v[72:73], v[108:109], v[170:171] op_sel:[0,1,0]
	v_pk_mul_f32 v[62:63], v[54:55], v[4:5] op_sel_hi:[1,0] neg_lo:[0,1] neg_hi:[0,1]
	v_pk_mul_f32 v[54:55], v[54:55], v[74:75] op_sel_hi:[1,0] neg_lo:[0,1] neg_hi:[0,1]
	v_pk_fma_f32 v[62:63], v[50:51], v[94:95], v[62:63]
	v_pk_fma_f32 v[50:51], v[50:51], v[102:103], v[54:55]
	v_pk_fma_f32 v[114:115], v[58:59], v[108:109], v[62:63] op_sel_hi:[1,0,1]
	v_pk_fma_f32 v[116:117], v[58:59], v[108:109], v[50:51] op_sel:[0,1,0]
	v_pk_mul_f32 v[50:51], v[56:57], v[4:5] op_sel_hi:[1,0] neg_lo:[0,1] neg_hi:[0,1]
	v_pk_mul_f32 v[170:171], v[56:57], v[74:75] op_sel_hi:[1,0] neg_lo:[0,1] neg_hi:[0,1]
	v_pk_fma_f32 v[50:51], v[52:53], v[96:97], v[50:51]
	v_pk_fma_f32 v[170:171], v[52:53], v[104:105], v[170:171]
	v_pk_fma_f32 v[118:119], v[60:61], v[108:109], v[50:51] op_sel_hi:[1,0,1]
	v_pk_fma_f32 v[120:121], v[60:61], v[108:109], v[170:171] op_sel:[0,1,0]
	v_pk_mul_f32 v[50:51], v[48:49], v[110:111]
	v_pk_mul_f32 v[48:49], v[48:49], v[112:113]
	v_pk_fma_f32 v[50:51], v[46:47], v[106:107], v[50:51]
	v_pk_fma_f32 v[46:47], v[46:47], v[98:99], v[48:49]
	v_pk_fma_f32 v[48:49], v[44:45], v[118:119], v[50:51]
	v_pk_fma_f32 v[44:45], v[44:45], v[120:121], v[46:47]
	v_pk_fma_f32 v[48:49], v[42:43], v[114:115], v[48:49]
	v_pk_fma_f32 v[42:43], v[42:43], v[116:117], v[44:45]
	v_add_f32_e32 v159, v48, v49
	v_add_f32_e32 v160, v42, v43
	s_waitcnt lgkmcnt(6)
	v_pk_mul_f32 v[92:93], v[40:41], v[110:111]
	v_pk_mul_f32 v[40:41], v[40:41], v[112:113]
	v_pk_fma_f32 v[92:93], v[38:39], v[106:107], v[92:93]
	v_pk_fma_f32 v[38:39], v[38:39], v[98:99], v[40:41]
	s_waitcnt lgkmcnt(5)
	v_pk_fma_f32 v[40:41], v[36:37], v[118:119], v[92:93]
	v_pk_fma_f32 v[36:37], v[36:37], v[120:121], v[38:39]
	v_pk_fma_f32 v[40:41], v[34:35], v[114:115], v[40:41]
	v_pk_fma_f32 v[34:35], v[34:35], v[116:117], v[36:37]
	v_add_f32_e32 v4, v40, v41
	v_add_f32_e32 v34, v34, v35
	s_waitcnt lgkmcnt(0)
	v_add_f32_dpp v4, v4, v4 quad_perm:[1,0,3,2] row_mask:0xf bank_mask:0xf bound_ctrl:1
	v_add_f32_dpp v34, v34, v34 quad_perm:[1,0,3,2] row_mask:0xf bank_mask:0xf bound_ctrl:1
	ds_read_b128 v[62:65], v235 offset:512
	ds_read_b128 v[50:53], v235 offset:528
	ds_read_b128 v[78:81], v235 offset:8704
	ds_read_b128 v[74:77], v235 offset:8720
	ds_read_b128 v[66:69], v235 offset:16896
	ds_read_b128 v[54:57], v235 offset:16912
	ds_read_b128 v[70:73], v235 offset:25088
	ds_read_b128 v[58:61], v235 offset:25104
	ds_read_b128 v[46:49], v235 offset:33280
	ds_read_b128 v[42:45], v235 offset:33296
	ds_read2_b32 v[96:97], v186 offset0:128 offset1:160
	v_add_f32_dpp v4, v4, v4 quad_perm:[2,3,0,1] row_mask:0xf bank_mask:0xf bound_ctrl:1
	v_add_f32_dpp v34, v34, v34 quad_perm:[2,3,0,1] row_mask:0xf bank_mask:0xf bound_ctrl:1
	s_nop 0
	v_add_f32_dpp v4, v4, v4 row_half_mirror row_mask:0xf bank_mask:0xf bound_ctrl:1
	v_add_f32_dpp v34, v34, v34 row_half_mirror row_mask:0xf bank_mask:0xf bound_ctrl:1
	v_pk_mul_f32 v[38:39], v[26:27], v[4:5] op_sel_hi:[1,0] neg_lo:[0,1] neg_hi:[0,1]
	v_pk_mul_f32 v[26:27], v[26:27], v[34:35] op_sel_hi:[1,0] neg_lo:[0,1] neg_hi:[0,1]
	v_pk_fma_f32 v[38:39], v[22:23], v[106:107], v[38:39]
	v_pk_fma_f32 v[22:23], v[22:23], v[98:99], v[26:27]
	v_pk_fma_f32 v[92:93], v[30:31], v[90:91], v[38:39] op_sel_hi:[1,0,1]
	v_pk_fma_f32 v[94:95], v[30:31], v[90:91], v[22:23] op_sel:[0,1,0]
	v_pk_mul_f32 v[22:23], v[28:29], v[4:5] op_sel_hi:[1,0] neg_lo:[0,1] neg_hi:[0,1]
	v_pk_mul_f32 v[170:171], v[28:29], v[34:35] op_sel_hi:[1,0] neg_lo:[0,1] neg_hi:[0,1]
	v_pk_fma_f32 v[22:23], v[24:25], v[110:111], v[22:23]
	v_pk_fma_f32 v[170:171], v[24:25], v[112:113], v[170:171]
	v_pk_fma_f32 v[100:101], v[32:33], v[90:91], v[22:23] op_sel_hi:[1,0,1]
	v_pk_fma_f32 v[102:103], v[32:33], v[90:91], v[170:171] op_sel:[0,1,0]
	v_pk_mul_f32 v[22:23], v[14:15], v[4:5] op_sel_hi:[1,0] neg_lo:[0,1] neg_hi:[0,1]
	v_pk_mul_f32 v[14:15], v[14:15], v[34:35] op_sel_hi:[1,0] neg_lo:[0,1] neg_hi:[0,1]
	v_pk_fma_f32 v[22:23], v[10:11], v[114:115], v[22:23]
	v_pk_fma_f32 v[10:11], v[10:11], v[116:117], v[14:15]
	v_pk_fma_f32 v[104:105], v[18:19], v[90:91], v[22:23] op_sel_hi:[1,0,1]
	v_pk_fma_f32 v[108:109], v[18:19], v[90:91], v[10:11] op_sel:[0,1,0]
	v_pk_mul_f32 v[10:11], v[16:17], v[4:5] op_sel_hi:[1,0] neg_lo:[0,1] neg_hi:[0,1]
	v_pk_mul_f32 v[170:171], v[16:17], v[34:35] op_sel_hi:[1,0] neg_lo:[0,1] neg_hi:[0,1]
	v_pk_fma_f32 v[10:11], v[12:13], v[118:119], v[10:11]
	v_pk_fma_f32 v[170:171], v[12:13], v[120:121], v[170:171]
	v_pk_fma_f32 v[110:111], v[20:21], v[90:91], v[10:11] op_sel_hi:[1,0,1]
	v_pk_fma_f32 v[112:113], v[20:21], v[90:91], v[170:171] op_sel:[0,1,0]
	v_pk_mul_f32 v[10:11], v[8:9], v[100:101]
	v_pk_mul_f32 v[8:9], v[8:9], v[102:103]
	v_pk_fma_f32 v[10:11], v[6:7], v[92:93], v[10:11]
	v_pk_fma_f32 v[6:7], v[6:7], v[94:95], v[8:9]
	v_pk_fma_f32 v[8:9], v[2:3], v[110:111], v[10:11]
	v_pk_fma_f32 v[2:3], v[2:3], v[112:113], v[6:7]
	v_pk_fma_f32 v[8:9], v[0:1], v[104:105], v[8:9]
	v_pk_fma_f32 v[0:1], v[0:1], v[108:109], v[2:3]
	v_add_f32_e32 v161, v8, v9
	v_add_f32_e32 v162, v0, v1
	s_waitcnt lgkmcnt(6)
; __device__ __forceinline__ void phase_rwkv(KP P, int l_, unsigned char* shm) {
;     ...
;                 f32x4 Aw0, Aw1, Akk0, Akk1, Ab0, Ab1, Ak0, Ak1, Ar0, Ar1; float Ava, Avb;
;                 f32x4 Bw0, Bw1, Bkk0, Bkk1, Bb0, Bb1, Bk0, Bk1, Br0, Br1; float Bva, Bvb;
;                 RW_LD(A, 0);
; #pragma unroll 2
;                 for (int tl = 0; tl < T; tl += 2) {
;                     RW_LD(B, tl + 1);
;                     RW_STEP(A, tl);
;                     RW_LD(A, tl + 2);
;                     RW_STEP(B, tl + 1);
;                 }
	v_pk_mul_f32 v[90:91], v[80:81], v[100:101]
	v_pk_mul_f32 v[80:81], v[80:81], v[102:103]
	v_pk_fma_f32 v[90:91], v[78:79], v[92:93], v[90:91]
	v_pk_fma_f32 v[78:79], v[78:79], v[94:95], v[80:81]
	s_waitcnt lgkmcnt(5)
	v_pk_fma_f32 v[80:81], v[76:77], v[110:111], v[90:91]
	v_pk_fma_f32 v[76:77], v[76:77], v[112:113], v[78:79]
	v_pk_fma_f32 v[80:81], v[74:75], v[104:105], v[80:81]
	v_pk_fma_f32 v[74:75], v[74:75], v[108:109], v[76:77]
	v_add_f32_e32 v76, v80, v81
	v_add_f32_e32 v74, v74, v75
	s_waitcnt lgkmcnt(0)
	v_mov_b32_e32 v78, v97
	v_add_f32_dpp v75, v76, v76 quad_perm:[1,0,3,2] row_mask:0xf bank_mask:0xf bound_ctrl:1
	v_add_f32_dpp v74, v74, v74 quad_perm:[1,0,3,2] row_mask:0xf bank_mask:0xf bound_ctrl:1
	ds_read_b128 v[10:13], v235 offset:768
	ds_read_b128 v[0:3], v235 offset:784
	ds_read_b128 v[38:41], v235 offset:8960
	ds_read_b128 v[34:37], v235 offset:8976
	ds_read_b128 v[26:29], v235 offset:17152
	ds_read_b128 v[6:9], v235 offset:17168
	ds_read2_b32 v[106:107], v186 offset0:192 offset1:224
	ds_read_b128 v[30:33], v235 offset:25344
	ds_read_b128 v[22:25], v235 offset:25360
	ds_read_b128 v[18:21], v235 offset:33536
	ds_read_b128 v[14:17], v235 offset:33552
	v_add_f32_dpp v75, v75, v75 quad_perm:[2,3,0,1] row_mask:0xf bank_mask:0xf bound_ctrl:1
	v_add_f32_dpp v76, v74, v74 quad_perm:[2,3,0,1] row_mask:0xf bank_mask:0xf bound_ctrl:1
	s_waitcnt lgkmcnt(4)
	v_add_f32_dpp v74, v75, v75 row_half_mirror row_mask:0xf bank_mask:0xf bound_ctrl:1
	v_add_f32_dpp v76, v76, v76 row_half_mirror row_mask:0xf bank_mask:0xf bound_ctrl:1
	v_pk_mul_f32 v[80:81], v[66:67], v[74:75] op_sel_hi:[1,0] neg_lo:[0,1] neg_hi:[0,1]
	v_pk_mul_f32 v[66:67], v[66:67], v[76:77] op_sel_hi:[1,0] neg_lo:[0,1] neg_hi:[0,1]
	v_pk_fma_f32 v[80:81], v[62:63], v[92:93], v[80:81]
	v_pk_fma_f32 v[62:63], v[62:63], v[94:95], v[66:67]
	v_pk_fma_f32 v[90:91], v[70:71], v[96:97], v[80:81] op_sel_hi:[1,0,1]
	v_pk_fma_f32 v[98:99], v[70:71], v[78:79], v[62:63] op_sel_hi:[1,0,1]
	v_pk_mul_f32 v[62:63], v[68:69], v[74:75] op_sel_hi:[1,0] neg_lo:[0,1] neg_hi:[0,1]
	v_pk_mul_f32 v[170:171], v[68:69], v[76:77] op_sel_hi:[1,0] neg_lo:[0,1] neg_hi:[0,1]
	v_pk_fma_f32 v[62:63], v[64:65], v[100:101], v[62:63]
	v_pk_fma_f32 v[170:171], v[64:65], v[102:103], v[170:171]
	v_pk_fma_f32 v[92:93], v[72:73], v[96:97], v[62:63] op_sel_hi:[1,0,1]
	v_pk_fma_f32 v[100:101], v[72:73], v[78:79], v[170:171] op_sel_hi:[1,0,1]
	v_pk_mul_f32 v[62:63], v[54:55], v[74:75] op_sel_hi:[1,0] neg_lo:[0,1] neg_hi:[0,1]
	v_pk_mul_f32 v[54:55], v[54:55], v[76:77] op_sel_hi:[1,0] neg_lo:[0,1] neg_hi:[0,1]
	v_pk_fma_f32 v[62:63], v[50:51], v[104:105], v[62:63]
	v_pk_fma_f32 v[50:51], v[50:51], v[108:109], v[54:55]
	v_pk_fma_f32 v[94:95], v[58:59], v[96:97], v[62:63] op_sel_hi:[1,0,1]
	v_pk_fma_f32 v[102:103], v[58:59], v[78:79], v[50:51] op_sel_hi:[1,0,1]
	v_pk_mul_f32 v[50:51], v[56:57], v[74:75] op_sel_hi:[1,0] neg_lo:[0,1] neg_hi:[0,1]
	v_pk_mul_f32 v[170:171], v[56:57], v[76:77] op_sel_hi:[1,0] neg_lo:[0,1] neg_hi:[0,1]
	v_pk_fma_f32 v[50:51], v[52:53], v[110:111], v[50:51]
	v_pk_fma_f32 v[170:171], v[52:53], v[112:113], v[170:171]
	v_pk_fma_f32 v[96:97], v[60:61], v[96:97], v[50:51] op_sel_hi:[1,0,1]
	v_pk_fma_f32 v[104:105], v[60:61], v[78:79], v[170:171] op_sel_hi:[1,0,1]
	v_pk_mul_f32 v[50:51], v[48:49], v[92:93]
	v_pk_mul_f32 v[48:49], v[48:49], v[100:101]
	v_pk_fma_f32 v[50:51], v[46:47], v[90:91], v[50:51]
	v_pk_fma_f32 v[46:47], v[46:47], v[98:99], v[48:49]
	v_pk_fma_f32 v[48:49], v[44:45], v[96:97], v[50:51]
	v_pk_fma_f32 v[44:45], v[44:45], v[104:105], v[46:47]
	v_pk_fma_f32 v[48:49], v[42:43], v[94:95], v[48:49]
	v_pk_fma_f32 v[42:43], v[42:43], v[102:103], v[44:45]
	v_add_f32_e32 v163, v48, v49
	v_add_f32_e32 v164, v42, v43
	v_cndmask_b32_e64 v166, v159, v157, s[98:99]
	v_cndmask_b32_e64 v168, v163, v161, s[98:99]
	v_cndmask_b32_e64 v172, v160, v158, s[98:99]
	v_cndmask_b32_e64 v240, v164, v162, s[98:99]
	v_cndmask_b32_e64 v165, v157, v159, s[98:99]
	v_cndmask_b32_e64 v167, v161, v163, s[98:99]
	v_cndmask_b32_e64 v169, v158, v160, s[98:99]
	v_cndmask_b32_e64 v187, v162, v164, s[98:99]
	v_add_f32_dpp v165, v166, v165 quad_perm:[1,0,3,2] row_mask:0xf bank_mask:0xf bound_ctrl:1
	v_add_f32_dpp v167, v168, v167 quad_perm:[1,0,3,2] row_mask:0xf bank_mask:0xf bound_ctrl:1
	v_add_f32_dpp v169, v172, v169 quad_perm:[1,0,3,2] row_mask:0xf bank_mask:0xf bound_ctrl:1
	v_add_f32_dpp v187, v240, v187 quad_perm:[1,0,3,2] row_mask:0xf bank_mask:0xf bound_ctrl:1
	v_cndmask_b32_e64 v166, v167, v165, s[100:101]
	v_cndmask_b32_e64 v172, v187, v169, s[100:101]
	v_cndmask_b32_e64 v165, v165, v167, s[100:101]
	v_cndmask_b32_e64 v169, v169, v187, s[100:101]
	v_add_f32_dpp v165, v166, v165 quad_perm:[2,3,0,1] row_mask:0xf bank_mask:0xf bound_ctrl:1
	v_add_f32_dpp v169, v172, v169 quad_perm:[2,3,0,1] row_mask:0xf bank_mask:0xf bound_ctrl:1
	s_nop 0
	v_add_f32_dpp v165, v165, v165 row_shr:4 row_mask:0xf bank_mask:0xf bound_ctrl:1
	v_add_f32_dpp v169, v169, v169 row_shr:4 row_mask:0xf bank_mask:0xf bound_ctrl:1
	s_mov_b64 s[72:73], exec
	s_mov_b32 exec_lo, 0xf0f0f0f0
	s_mov_b32 exec_hi, 0xf0f0f0f0
	ds_write_b32 v253, v165
	ds_write_b32 v253, v169 offset:128
	s_mov_b64 exec, s[72:73]
	s_branch .LBB0_2516
